# G1 next-unit decode: float-division (v_rcp/v_trunc/readfirstlane) replaced by shift/mask SALU computing the same (pm,pn) mapping, both decode sites
# speedup vs baseline: 1.0046x; 1.0046x over previous
; __host__ __device__ __forceinline__ int xcd_remap(int L, int nwg) { const int q = nwg / NXCD, r = nwg % NXCD, xcd = L % NXCD, off = L / NXCD; return (xcd < r ? xcd * (q + 1) : r * (q + 1) + (xcd - r) * q) + off; }
; __host__ __device__ __forceinline__ bool order_mn(int L, int nM, int nN, Unit& u) {
;     const int nwg = nM * nN; if (L >= nwg) return false;
;     const int wgid = xcd_remap(L, nwg);
;     const int nig = WGM * nN, gid = wgid / nig, fm = gid * WGM, gsz = (nM - fm) < WGM ? (nM - fm) : WGM;
;     u.pm = fm + ((wgid % nig) % gsz); u.pn = (wgid % nig) / gsz; u.g = 0; u.ks = 0; return true;
.LBB0_144:
	v_mov_b32_e32 v10, v0
	s_cmpk_lt_i32 s92, 0x1040
	s_cselect_b64 s[4:5], -1, 0
	s_cmpk_gt_i32 s92, 0x103f
	v_readfirstlane_b32 s18, v10
	s_cbranch_scc1 .LBB0_146
	s_ashr_i32 s2, s92, 31
	s_lshr_b32 s2, s2, 29
	s_add_i32 s2, s92, s2
	s_and_b32 s3, s2, -8
	s_sub_i32 s3, s92, s3
	s_cmp_lt_i32 s3, 0
	s_movk_i32 s6, 0x209
	s_cselect_b32 s6, s6, 0x208
	s_mul_i32 s3, s6, s3
	s_ashr_i32 s2, s2, 3
	s_add_i32 s2, s3, s2
	s_cmpk_lt_u32 s2, 0x1000
	s_cbranch_scc0 .Lg1o_ctx_a
	s_lshr_b32 s3, s2, 8
	s_lshl_b32 s3, s3, 3
	s_and_b32 s6, s2, 7
	s_add_i32 s80, s3, s6
	s_bfe_u32 s78, s2, 0x50003
	s_branch .Lg1o_done_a

;     __host__ __device__ bool unit(int L, Unit& u) const { return order_mn(L, RT / 256, 32, u); }
;     __host__ __device__ bool unit(int L, Unit& u) const { if (L >= NCHB / 256) return false; u.g = g; u.pm = 0; u.pn = b * (NCHB / 256) + L; u.ks = 0; return true; }
;     __host__ __device__ bool unit(int L, Unit& u) const { constexpr int nN = TP / 256, nM = NCHB / 256; if (L >= nN * nM) return false; u.g = g; u.pm = b * nM + L / nN; u.pn = L % nN; u.ks = 0; return true; }
;     __host__ __device__ bool unit(int L, Unit& u) const { return order_mn(L, RL / 256, 8, u); }
;     __host__ __device__ bool unit(int L, Unit& u) const { return order_mn(L, RL / 256, 4, u); }
; __host__ __device__ __forceinline__ int xcd_remap(int L, int nwg) { const int q = nwg / NXCD, r = nwg % NXCD, xcd = L % NXCD, off = L / NXCD; return (xcd < r ? xcd * (q + 1) : r * (q + 1) + (xcd - r) * q) + off; }
; __host__ __device__ __forceinline__ bool order_mn(int L, int nM, int nN, Unit& u) {
;     const int nwg = nM * nN; if (L >= nwg) return false;
;     const int wgid = xcd_remap(L, nwg);
;     const int nig = WGM * nN, gid = wgid / nig, fm = gid * WGM, gsz = (nM - fm) < WGM ? (nM - fm) : WGM;
;     u.pm = fm + ((wgid % nig) % gsz); u.pn = (wgid % nig) / gsz; u.g = 0; u.ks = 0; return true;
; template <class P>
; __device__ __forceinline__ void gemm_phase(LAS unsigned char* lds, const P& p, const int G, const int c) {
;     ...
;         const bool has_next = p.unit((ui + 1) * G + c, nxt);
.LBB0_152:
	s_add_i32 s44, s44, 1
	s_mul_i32 s18, s44, s84
	s_add_i32 s18, s18, s92
	s_cmpk_lt_i32 s18, 0x1040
	s_cselect_b64 s[70:71], -1, 0
	s_cmpk_gt_i32 s18, 0x103f
	s_cbranch_scc1 .LBB0_154
	s_ashr_i32 s19, s18, 31
	s_lshr_b32 s19, s19, 29
	s_add_i32 s19, s18, s19
	s_ashr_i32 s30, s19, 3
	s_and_b32 s19, s19, -8
	s_sub_i32 s18, s18, s19
	s_cmp_lt_i32 s18, 0
	s_movk_i32 s19, 0x209
	s_cselect_b32 s19, s19, 0x208
	s_mul_i32 s18, s19, s18
	s_add_i32 s18, s18, s30
	s_cmpk_lt_u32 s18, 0x1000
	s_cbranch_scc0 .Lg1o_ctx_b
	s_lshr_b32 s19, s18, 8
	s_lshl_b32 s19, s19, 3
	s_and_b32 s30, s18, 7
	s_add_i32 s68, s19, s30
	s_bfe_u32 s88, s18, 0x50003
	s_branch .Lg1o_done_b
